# norm_rows: next row's four loads issued before the current row's reduction (guarded cross-iteration prefetch)
# baseline (speedup 1.0000x reference)
; __device__ __forceinline__ void norm_rows(const float* src, bf16_t* xn, float* outf, const float* gain, unsigned* rs_out, int tid, int bid, int nbk) {
;     const int lane = tid & 63, wv = tid >> 6;
;     const int gw = bid * 8 + wv, NGW = nbk * 8;
;     for (int m = gw; m < MTOK; m += NGW) {
;         const float* xr = src + (size_t)m * DM + lane * 8;
;         f32x4 v[4]; float s = 0.f;
; #pragma unroll
;         for (int j = 0; j < 4; ++j) { v[j] = *(const f32x4*)(xr + (j >> 1) * 512 + (j & 1) * 4); s += (v[j][0] * v[j][0] + v[j][1] * v[j][1]) + (v[j][2] * v[j][2] + v[j][3] * v[j][3]); }
;         const float tot = wave_sum(s);
;         if (rs_out && lane == 0) rs_out[m] = (unsigned)(tot * 1024.f + 0.5f);
;         bf16_t* o = xn + (size_t)m * DM + lane * 8;
.LBB0_539:
	s_or_b64 exec, exec, s[48:49]
	s_add_i32 s12, s7, 16
	s_cmp_lt_u32 s12, 33
	s_mov_b32 s14, 0x8000
	s_cselect_b64 s[12:13], -1, 0
	v_cmp_gt_i32_e32 vcc, s14, v3
	s_and_b64 s[14:15], s[12:13], vcc
	s_and_saveexec_b64 s[12:13], s[14:15]
	s_cbranch_execz .LBB0_544
	v_and_b32_e32 v1, 64, v178
	v_add_u32_e32 v1, 64, v1
	v_xor_b32_e32 v4, 1, v178
	v_cmp_lt_i32_e32 vcc, v4, v1
	s_ashr_i32 s47, s46, 31
	s_waitcnt vmcnt(9)
	v_and_b32_e32 v8, 63, v187
	v_cndmask_b32_e32 v4, v178, v4, vcc
	s_waitcnt vmcnt(5)
	v_lshlrev_b32_e32 v24, 2, v4
	v_xor_b32_e32 v4, 2, v178
	v_cmp_lt_i32_e32 vcc, v4, v1
	v_readlane_b32 s14, v255, 35
	v_readlane_b32 s15, v255, 36
	v_cndmask_b32_e32 v4, v178, v4, vcc
	v_lshlrev_b32_e32 v25, 2, v4
	v_xor_b32_e32 v4, 4, v178
	v_cmp_lt_i32_e32 vcc, v4, v1
	s_ashr_i32 s45, s44, 31
	s_lshl_b64 s[42:43], s[44:45], 2
	v_cndmask_b32_e32 v4, v178, v4, vcc
	v_lshlrev_b32_e32 v26, 2, v4
	v_xor_b32_e32 v4, 8, v178
	v_cmp_lt_i32_e32 vcc, v4, v1
	s_lshl_b64 s[48:49], s[44:45], 12
	s_mov_b64 s[50:51], 0
	v_cndmask_b32_e32 v4, v178, v4, vcc
	v_lshlrev_b32_e32 v27, 2, v4
	v_xor_b32_e32 v4, 16, v178
	v_cmp_lt_i32_e32 vcc, v4, v1
	s_nop 1
	v_cndmask_b32_e32 v4, v178, v4, vcc
	s_waitcnt vmcnt(4)
	v_lshlrev_b32_e32 v28, 2, v4
	v_xor_b32_e32 v4, 32, v178
	v_cmp_lt_i32_e32 vcc, v4, v1
	s_nop 1
	v_cndmask_b32_e32 v1, v178, v4, vcc
	v_lshlrev_b32_e32 v29, 2, v1
	v_ashrrev_i32_e32 v1, 31, v0
	v_lshl_add_u64 v[4:5], v[0:1], 0, s[46:47]
	v_lshlrev_b64 v[6:7], 11, v[4:5]
	v_lshl_or_b32 v6, v8, 4, v6
	v_lshl_add_u64 v[0:1], v[4:5], 2, s[14:15]
	v_lshl_add_u64 v[6:7], s[60:61], 0, v[6:7]
	s_mov_b64 s[14:15], 0x3800400
	v_lshl_add_u64 v[20:21], v[6:7], 0, s[14:15]
	s_load_dwordx2 s[14:15], s[0:1], 0x0
	v_lshlrev_b64 v[4:5], 12, v[4:5]
	v_lshl_or_b32 v4, v8, 5, v4
	v_cmp_eq_u32_e32 vcc, 0, v8
	s_lshl_b64 s[46:47], s[44:45], 11
	s_waitcnt lgkmcnt(0)
	v_lshl_add_u64 v[22:23], s[14:15], 0, v[4:5]
	global_load_dwordx4 v[140:143], v[22:23], off
	global_load_dwordx4 v[144:147], v[22:23], off offset:16
	global_load_dwordx4 v[148:151], v[22:23], off offset:2048
	global_load_dwordx4 v[152:155], v[22:23], off offset:2064
	s_waitcnt vmcnt(0)
	s_branch .Lnr_body

; __device__ __forceinline__ void norm_rows(const float* src, bf16_t* xn, float* outf, const float* gain, unsigned* rs_out, int tid, int bid, int nbk) {
;     ...
;     for (int m = gw; m < MTOK; m += NGW) {
;         const float* xr = src + (size_t)m * DM + lane * 8;
;         f32x4 v[4]; float s = 0.f;
; #pragma unroll
;         for (int j = 0; j < 4; ++j) { v[j] = *(const f32x4*)(xr + (j >> 1) * 512 + (j & 1) * 4); s += (v[j][0] * v[j][0] + v[j][1] * v[j][1]) + (v[j][2] * v[j][2] + v[j][3] * v[j][3]); }
;         const float tot = wave_sum(s);
;         if (rs_out && lane == 0) rs_out[m] = (unsigned)(tot * 1024.f + 0.5f);
.LBB0_542:
	s_waitcnt vmcnt(2)
.Lnr_body:
	v_mov_b32_e32 v8, v140
	v_mov_b32_e32 v9, v141
	v_mov_b32_e32 v10, v142
	v_mov_b32_e32 v11, v143
	v_mov_b32_e32 v4, v144
	v_mov_b32_e32 v5, v145
	v_mov_b32_e32 v6, v146
	v_mov_b32_e32 v7, v147
	v_mov_b32_e32 v16, v148
	v_mov_b32_e32 v17, v149
	v_mov_b32_e32 v18, v150
	v_mov_b32_e32 v19, v151
	v_mov_b32_e32 v12, v152
	v_mov_b32_e32 v13, v153
	v_mov_b32_e32 v14, v154
	v_mov_b32_e32 v15, v155
	v_add_u32_e32 v138, s44, v3
	v_cmp_ge_i32_e64 s[100:101], s67, v138
	s_and_saveexec_b64 s[100:101], s[100:101]
	v_lshl_add_u64 v[138:139], v[22:23], 0, s[48:49]
	global_load_dwordx4 v[140:143], v[138:139], off
	global_load_dwordx4 v[144:147], v[138:139], off offset:16
	global_load_dwordx4 v[148:151], v[138:139], off offset:2048
	global_load_dwordx4 v[152:155], v[138:139], off offset:2064
	s_mov_b64 exec, s[100:101]
	v_mul_f32_e32 v30, v9, v9
	s_waitcnt lgkmcnt(0)
	v_mul_f32_e32 v31, v11, v11
	v_mul_f32_e32 v32, v5, v5
	v_mul_f32_e32 v33, v7, v7
	v_mul_f32_e32 v34, v17, v17
	v_mul_f32_e32 v35, v19, v19
	v_fmac_f32_e32 v30, v8, v8
	v_fmac_f32_e32 v31, v10, v10
	v_fmac_f32_e32 v32, v4, v4
	v_fmac_f32_e32 v33, v6, v6
	v_mul_f32_e32 v36, v13, v13
	v_mul_f32_e32 v37, v15, v15
	v_fmac_f32_e32 v34, v16, v16
	v_fmac_f32_e32 v35, v18, v18
	v_add_f32_e32 v30, v30, v31
	v_add_f32_e32 v31, v32, v33
	v_fmac_f32_e32 v36, v12, v12
	v_fmac_f32_e32 v37, v14, v14
	v_add_f32_e32 v32, v34, v35
	v_add_f32_e32 v30, v30, v31
	v_add_f32_e32 v30, v30, v32
	v_add_f32_e32 v31, v36, v37
	v_add_f32_e32 v30, v30, v31
	ds_bpermute_b32 v31, v24, v30
	s_waitcnt lgkmcnt(0)
	v_add_f32_e32 v30, v30, v31
	ds_bpermute_b32 v31, v25, v30
	s_waitcnt lgkmcnt(0)
	v_add_f32_e32 v30, v30, v31
	ds_bpermute_b32 v31, v26, v30
	s_waitcnt lgkmcnt(0)
	v_add_f32_e32 v30, v30, v31
	ds_bpermute_b32 v31, v27, v30
	s_waitcnt lgkmcnt(0)
	v_add_f32_e32 v30, v30, v31
	ds_bpermute_b32 v31, v28, v30
	s_waitcnt lgkmcnt(0)
	v_add_f32_e32 v30, v30, v31
	ds_bpermute_b32 v31, v29, v30
	s_and_saveexec_b64 s[40:41], vcc
	s_cbranch_execz .LBB0_541
	s_waitcnt lgkmcnt(0)
	v_add_f32_e32 v30, v30, v31
	v_fma_f32 v30, v30, s3, 0.5
	v_cvt_u32_f32_e32 v30, v30
	global_store_dword v[0:1], v30, off
	s_branch .LBB0_541
